# v7: + attention gate quotient z/(1+exp(-z)) computed in f32 as rcp + one Newton correction + v_div_fixup instead of the div_scale/div_fmas ladder
# speedup vs baseline: 1.0177x; 1.0039x over previous
; #define SBAR() __builtin_amdgcn_sched_barrier(0)
; __device__ __forceinline__ int crow(int r, int hi) { return (r & 3) + 8 * (r >> 2) + 4 * hi; }
; __device__ __forceinline__ void attn_body(const bf16_t* __restrict__ Qb, const bf16_t* __restrict__ Kh, const bf16_t* __restrict__ Vh, const bf16_t* __restrict__ Rh,
;                                           bf16_t* __restrict__ Zb, int seq, char* lds, int wv, bool nowrite) {
;     ...
;     if (hi == 0) li_l[r32] = l_reg; asm volatile("s_waitcnt lgkmcnt(0)" ::: "memory");
;     float rli[16];
; #pragma unroll
;     for (int r = 0; r < 16; ++r) rli[r] = __builtin_amdgcn_rcpf(li_l[crow(r, hi)]);
;     bf16_t* Zw = Zb + (long)(wid * QBLK + 4 * hi) * LDZ + r32;
;     unsigned short zq[16][4];
; #pragma unroll
;     for (int r = 0; r < 16; ++r)
; #pragma unroll
;         for (int d0 = 0; d0 < 4; ++d0) zq[r][d0] = Zw[(long)((r & 3) + 8 * (r >> 2)) * LDZ + d0 * 32];
;     asm volatile("s_waitcnt vmcnt(0)" ::: "memory"); SBAR();
.LBB0_602:
	s_or_b64 exec, exec, s[8:9]
	s_waitcnt lgkmcnt(0)
	v_add_u32_e32 v72, s1, v212
	ds_read_b128 v[64:67], v72
	ds_read_b128 v[68:71], v72 offset:32
	s_or_b64 s[6:7], s[42:43], s[24:25]
	s_lshl_b64 s[6:7], s[6:7], 12
	s_add_u32 s3, s77, s6
	s_waitcnt lgkmcnt(1)
	v_rcp_f32_e32 v170, v64
	v_rcp_f32_e32 v166, v65
	v_rcp_f32_e32 v159, v66
	v_rcp_f32_e32 v154, v67
	ds_read_b128 v[64:67], v72 offset:64
	s_addc_u32 s7, s78, s7
	s_lshl_b32 s2, s2, 1
	s_add_u32 s6, s3, s2
	v_lshl_or_b32 v212, v165, 2, s52
	s_waitcnt lgkmcnt(0)
	v_rcp_f32_e32 v127, v64
	v_rcp_f32_e32 v122, v65
	v_rcp_f32_e32 v116, v66
	v_rcp_f32_e32 v111, v67
	ds_read_b128 v[64:67], v72 offset:96
	s_addc_u32 s7, s7, 0
	s_movk_i32 s2, 0x1000
	v_rcp_f32_e32 v138, v70
	v_rcp_f32_e32 v132, v71
	s_waitcnt lgkmcnt(0)
	v_rcp_f32_e32 v105, v64
	v_rcp_f32_e32 v100, v65
	v_lshlrev_b64 v[64:65], 12, v[212:213]
	v_lshl_add_u64 v[64:65], s[6:7], 0, v[64:65]
	v_lshlrev_b32_e32 v212, 1, v164
	v_lshl_add_u64 v[94:95], v[64:65], 0, v[212:213]
	v_add_co_u32_e32 v92, vcc, s2, v94
	s_movk_i32 s2, 0x2000
	s_nop 0
	v_addc_co_u32_e32 v93, vcc, 0, v95, vcc
	v_add_co_u32_e32 v90, vcc, s2, v94
	s_movk_i32 s2, 0x3000
	s_nop 0
	v_addc_co_u32_e32 v91, vcc, 0, v95, vcc
	v_add_co_u32_e32 v88, vcc, s2, v94
	s_mov_b32 s2, 0x8000
	s_nop 0
	v_addc_co_u32_e32 v89, vcc, 0, v95, vcc
	v_add_co_u32_e32 v86, vcc, s2, v94
	s_mov_b32 s2, 0x9000
	s_nop 0
	v_addc_co_u32_e32 v87, vcc, 0, v95, vcc
	v_add_co_u32_e32 v84, vcc, s2, v94
	s_mov_b32 s2, 0xa000
	s_nop 0
	v_addc_co_u32_e32 v85, vcc, 0, v95, vcc
	v_add_co_u32_e32 v82, vcc, s2, v94
	s_mov_b32 s2, 0xb000
	s_nop 0
	v_addc_co_u32_e32 v83, vcc, 0, v95, vcc
	v_add_co_u32_e32 v80, vcc, s2, v94
	s_mov_b32 s2, 0x11000
	s_nop 0
	v_addc_co_u32_e32 v81, vcc, 0, v95, vcc
	v_add_co_u32_e32 v78, vcc, s87, v94
	v_rcp_f32_e32 v149, v68
	s_nop 0
	v_addc_co_u32_e32 v79, vcc, 0, v95, vcc
	v_add_co_u32_e32 v76, vcc, s2, v94
	s_mov_b32 s2, 0x12000
	s_nop 0
	v_addc_co_u32_e32 v77, vcc, 0, v95, vcc
	v_add_co_u32_e32 v74, vcc, s2, v94
	s_mov_b32 s2, 0x13000
	s_nop 0
	v_addc_co_u32_e32 v75, vcc, 0, v95, vcc
	v_add_co_u32_e32 v72, vcc, s2, v94
	s_mov_b32 s2, 0x18000
	s_nop 0
	v_addc_co_u32_e32 v73, vcc, 0, v95, vcc
	v_add_co_u32_e32 v70, vcc, s2, v94
	s_mov_b32 s2, 0x19000
	s_nop 0
	v_addc_co_u32_e32 v71, vcc, 0, v95, vcc
	v_add_co_u32_e32 v68, vcc, s2, v94
	v_rcp_f32_e32 v143, v69
	s_nop 0
	v_addc_co_u32_e32 v69, vcc, 0, v95, vcc
	s_mov_b32 s2, 0x1a000
	v_rcp_f32_e32 v97, v66
	v_add_co_u32_e32 v66, vcc, s2, v94
	v_rcp_f32_e32 v96, v67
	s_nop 0
	v_addc_co_u32_e32 v67, vcc, 0, v95, vcc
	s_mov_b32 s2, 0x1b000
	v_add_co_u32_e32 v64, vcc, s2, v94
	global_load_ushort v175, v[94:95], off
	global_load_ushort v174, v[94:95], off offset:64
	global_load_ushort v173, v[94:95], off offset:128
	global_load_ushort v172, v[94:95], off offset:192
	v_addc_co_u32_e32 v65, vcc, 0, v95, vcc
	global_load_ushort v171, v[90:91], off offset:-4096
	global_load_ushort v169, v[92:93], off offset:64
	global_load_ushort v168, v[92:93], off offset:128
	global_load_ushort v167, v[92:93], off offset:192
	global_load_ushort v165, v[90:91], off
	global_load_ushort v164, v[90:91], off offset:64
	global_load_ushort v163, v[90:91], off offset:128
	global_load_ushort v162, v[90:91], off offset:192
	global_load_ushort v161, v[88:89], off
	global_load_ushort v160, v[88:89], off offset:64
	global_load_ushort v158, v[88:89], off offset:128
	global_load_ushort v157, v[88:89], off offset:192
	global_load_ushort v156, v[84:85], off offset:-4096
	global_load_ushort v155, v[86:87], off offset:64
	global_load_ushort v153, v[86:87], off offset:128
	global_load_ushort v152, v[86:87], off offset:192
	global_load_ushort v151, v[84:85], off
	global_load_ushort v150, v[84:85], off offset:64
	global_load_ushort v148, v[84:85], off offset:128
	global_load_ushort v147, v[84:85], off offset:192
	global_load_ushort v146, v[80:81], off offset:-4096
	global_load_ushort v145, v[82:83], off offset:64
	global_load_ushort v144, v[82:83], off offset:128
	global_load_ushort v142, v[82:83], off offset:192
	global_load_ushort v141, v[80:81], off
	global_load_ushort v140, v[80:81], off offset:64
	global_load_ushort v139, v[80:81], off offset:128
	global_load_ushort v137, v[80:81], off offset:192
	global_load_ushort v136, v[76:77], off offset:-4096
	global_load_ushort v135, v[78:79], off offset:64
	global_load_ushort v134, v[78:79], off offset:128
	global_load_ushort v133, v[78:79], off offset:192
	global_load_ushort v131, v[76:77], off
	global_load_ushort v130, v[76:77], off offset:64
	global_load_ushort v129, v[76:77], off offset:128
	global_load_ushort v128, v[76:77], off offset:192
	global_load_ushort v126, v[72:73], off offset:-4096
	global_load_ushort v125, v[74:75], off offset:64
	global_load_ushort v124, v[74:75], off offset:128
	global_load_ushort v123, v[74:75], off offset:192
	global_load_ushort v121, v[72:73], off
	global_load_ushort v120, v[72:73], off offset:64
	global_load_ushort v119, v[72:73], off offset:128
	global_load_ushort v118, v[72:73], off offset:192
	global_load_ushort v117, v[68:69], off offset:-4096
	global_load_ushort v115, v[70:71], off offset:64
	global_load_ushort v114, v[70:71], off offset:128
	global_load_ushort v113, v[70:71], off offset:192
	global_load_ushort v112, v[68:69], off
	global_load_ushort v110, v[68:69], off offset:64
	global_load_ushort v109, v[68:69], off offset:128
	global_load_ushort v108, v[68:69], off offset:192
	global_load_ushort v107, v[64:65], off offset:-4096
	global_load_ushort v106, v[66:67], off offset:64
	global_load_ushort v104, v[66:67], off offset:128
	global_load_ushort v103, v[66:67], off offset:192
	global_load_ushort v102, v[64:65], off
	global_load_ushort v101, v[64:65], off offset:64
	global_load_ushort v99, v[64:65], off offset:128
	global_load_ushort v98, v[64:65], off offset:192
	s_waitcnt vmcnt(0)
; __device__ __forceinline__ unsigned cvt_pk_bf16(float lo, float hi) { unsigned r; asm volatile("v_cvt_pk_bf16_f32 %0, %1, %2" : "=v"(r) : "v"(lo), "v"(hi)); return r; }
; __device__ __forceinline__ float bf2f(unsigned short b) { return __uint_as_float(((unsigned)b) << 16); }
; __device__ __forceinline__ float silu_f(float z) { return z / (1.f + __expf(-z)); }
; __device__ __forceinline__ void attn_body(const bf16_t* __restrict__ Qb, const bf16_t* __restrict__ Kh, const bf16_t* __restrict__ Vh, const bf16_t* __restrict__ Rh,
;                                           bf16_t* __restrict__ Zb, int seq, char* lds, int wv, bool nowrite) {
;     ...
; #pragma unroll
;     for (int r = 0; r < 16; ++r) {
; #pragma unroll
;         for (int d0 = 0; d0 < 4; ++d0) { const float z = bf2f(zq[r][d0]);
;             if (!nowrite) Zw[(long)((r & 3) + 8 * (r >> 2)) * LDZ + d0 * 32] = (bf16_t)(cvt_pk_bf16(o[d0][r] * rli[r] * silu_f(z), 0.f) & 0xffffu); } }
	s_waitcnt vmcnt(62)
	v_lshlrev_b32_e32 v175, 16, v175
	v_mul_f32_e32 v176, 0xbfb8aa3b, v175
	v_exp_f32_e32 v176, v176
	v_mul_f32_e32 v0, v0, v170
	v_mul_f32_e32 v48, v48, v170
	v_mul_f32_e32 v32, v32, v170
	v_add_f32_e32 v176, 1.0, v176
	v_mul_f32_e32 v16, v16, v170
	v_mul_f32_e32 v1, v1, v166
	s_add_i32 s79, s79, 1
	v_rcp_f32_e32 v178, v176
	s_nop 0
	v_mul_f32_e32 v180, v175, v178
	v_fma_f32 v177, -v176, v180, v175
	v_fmac_f32_e32 v180, v177, v178
	v_div_fixup_f32 v175, v180, v176, v175
	v_mul_f32_e32 v0, v0, v175
	v_cvt_pk_bf16_f32 v0, v0, v213
	global_store_short v[94:95], v0, off
	v_lshlrev_b32_e32 v0, 16, v174
	v_mul_f32_e32 v174, 0xbfb8aa3b, v0
	v_exp_f32_e32 v174, v174
	s_cmp_eq_u32 s79, s34
	v_add_f32_e32 v174, 1.0, v174
	v_rcp_f32_e32 v176, v174
	s_nop 0
	v_mul_f32_e32 v178, v0, v176
	v_fma_f32 v175, -v174, v178, v0
	v_fmac_f32_e32 v178, v175, v176
	v_div_fixup_f32 v0, v178, v174, v0
	v_mul_f32_e32 v0, v48, v0
	v_cvt_pk_bf16_f32 v0, v0, v213
	global_store_short v[94:95], v0, off offset:64
	s_waitcnt vmcnt(62)
	v_lshlrev_b32_e32 v0, 16, v173
	v_mul_f32_e32 v48, 0xbfb8aa3b, v0
	v_exp_f32_e32 v48, v48
	s_nop 0
	v_add_f32_e32 v48, 1.0, v48
	v_rcp_f32_e32 v174, v48
	s_nop 0
	v_mul_f32_e32 v176, v0, v174
	v_fma_f32 v173, -v48, v176, v0
	v_fmac_f32_e32 v176, v173, v174
	v_div_fixup_f32 v0, v176, v48, v0
	v_mul_f32_e32 v0, v32, v0
	v_cvt_pk_bf16_f32 v0, v0, v213
	global_store_short v[94:95], v0, off offset:128
	v_lshlrev_b32_e32 v0, 16, v172
	v_mul_f32_e32 v32, 0xbfb8aa3b, v0
	v_exp_f32_e32 v32, v32
	s_nop 0
	v_add_f32_e32 v32, 1.0, v32
	v_rcp_f32_e32 v170, v32
	s_nop 0
	v_mul_f32_e32 v173, v0, v170
	v_fma_f32 v48, -v32, v173, v0
	v_fmac_f32_e32 v173, v48, v170
	v_div_fixup_f32 v0, v173, v32, v0
	v_mul_f32_e32 v0, v16, v0
	v_cvt_pk_bf16_f32 v0, v0, v213
	global_store_short v[94:95], v0, off offset:192
	s_waitcnt vmcnt(62)
	v_lshlrev_b32_e32 v0, 16, v171
	v_mul_f32_e32 v16, 0xbfb8aa3b, v0
	v_exp_f32_e32 v16, v16
	s_nop 0
	v_add_f32_e32 v16, 1.0, v16
	v_rcp_f32_e32 v48, v16
	s_nop 0
	v_mul_f32_e32 v95, v0, v48
	v_fma_f32 v32, -v16, v95, v0
	v_fmac_f32_e32 v95, v32, v48
	v_div_fixup_f32 v0, v95, v16, v0
	v_mul_f32_e32 v0, v1, v0
	v_cvt_pk_bf16_f32 v0, v0, v213
	global_store_short v[90:91], v0, off offset:-4096
	v_lshlrev_b32_e32 v0, 16, v169
	v_mul_f32_e32 v16, 0xbfb8aa3b, v0
	v_exp_f32_e32 v16, v16
	v_mul_f32_e32 v1, v49, v166
	v_add_f32_e32 v16, 1.0, v16
	v_rcp_f32_e32 v48, v16
	s_nop 0
	v_mul_f32_e32 v94, v0, v48
	v_fma_f32 v32, -v16, v94, v0
	v_fmac_f32_e32 v94, v32, v48
	v_div_fixup_f32 v0, v94, v16, v0
	v_mul_f32_e32 v0, v1, v0
	v_cvt_pk_bf16_f32 v0, v0, v213
	global_store_short v[92:93], v0, off offset:64
	s_waitcnt vmcnt(62)
	v_lshlrev_b32_e32 v0, 16, v168
	v_mul_f32_e32 v16, 0xbfb8aa3b, v0
	v_exp_f32_e32 v16, v16
	v_mul_f32_e32 v1, v33, v166
	v_add_f32_e32 v16, 1.0, v16
	v_rcp_f32_e32 v33, v16
	s_nop 0
	v_mul_f32_e32 v49, v0, v33
	v_fma_f32 v32, -v16, v49, v0
	v_fmac_f32_e32 v49, v32, v33
	v_div_fixup_f32 v0, v49, v16, v0
	v_mul_f32_e32 v0, v1, v0
	v_cvt_pk_bf16_f32 v0, v0, v213
	global_store_short v[92:93], v0, off offset:128
	v_lshlrev_b32_e32 v0, 16, v167
	v_mul_f32_e32 v16, 0xbfb8aa3b, v0
	v_exp_f32_e32 v16, v16
	v_mul_f32_e32 v1, v17, v166
	v_add_f32_e32 v16, 1.0, v16
	v_rcp_f32_e32 v32, v16
	s_nop 0
	v_mul_f32_e32 v48, v0, v32
	v_fma_f32 v17, -v16, v48, v0
	v_fmac_f32_e32 v48, v17, v32
	v_div_fixup_f32 v0, v48, v16, v0
	v_mul_f32_e32 v0, v1, v0
	v_cvt_pk_bf16_f32 v0, v0, v213
	global_store_short v[92:93], v0, off offset:192
	s_waitcnt vmcnt(62)
	v_lshlrev_b32_e32 v0, 16, v165
	v_mul_f32_e32 v1, v2, v159
	v_mul_f32_e32 v2, 0xbfb8aa3b, v0
	v_exp_f32_e32 v2, v2
	s_nop 0
	v_add_f32_e32 v2, 1.0, v2
	v_rcp_f32_e32 v17, v2
	s_nop 0
	v_mul_f32_e32 v33, v0, v17
	v_fma_f32 v16, -v2, v33, v0
	v_fmac_f32_e32 v33, v16, v17
	v_div_fixup_f32 v0, v33, v2, v0
	v_mul_f32_e32 v0, v1, v0
	v_cvt_pk_bf16_f32 v0, v0, v213
	global_store_short v[90:91], v0, off
	v_lshlrev_b32_e32 v0, 16, v164
	v_mul_f32_e32 v2, 0xbfb8aa3b, v0
	v_exp_f32_e32 v2, v2
	v_mul_f32_e32 v1, v50, v159
	v_add_f32_e32 v2, 1.0, v2
	v_rcp_f32_e32 v17, v2
	s_nop 0
	v_mul_f32_e32 v33, v0, v17
	v_fma_f32 v16, -v2, v33, v0
	v_fmac_f32_e32 v33, v16, v17
	v_div_fixup_f32 v0, v33, v2, v0
	v_mul_f32_e32 v0, v1, v0
	v_cvt_pk_bf16_f32 v0, v0, v213
	global_store_short v[90:91], v0, off offset:64
	s_waitcnt vmcnt(62)
	v_lshlrev_b32_e32 v0, 16, v163
	v_mul_f32_e32 v2, 0xbfb8aa3b, v0
	v_exp_f32_e32 v2, v2
	v_mul_f32_e32 v1, v34, v159
	v_add_f32_e32 v2, 1.0, v2
	v_rcp_f32_e32 v17, v2
	s_nop 0
	v_mul_f32_e32 v33, v0, v17
	v_fma_f32 v16, -v2, v33, v0
	v_fmac_f32_e32 v33, v16, v17
	v_div_fixup_f32 v0, v33, v2, v0
	v_mul_f32_e32 v0, v1, v0
	v_cvt_pk_bf16_f32 v0, v0, v213
	global_store_short v[90:91], v0, off offset:128
	v_lshlrev_b32_e32 v0, 16, v162
	v_mul_f32_e32 v2, 0xbfb8aa3b, v0
	v_exp_f32_e32 v2, v2
	v_mul_f32_e32 v1, v18, v159
	v_add_f32_e32 v2, 1.0, v2
	v_rcp_f32_e32 v17, v2
	s_nop 0
	v_mul_f32_e32 v32, v0, v17
	v_fma_f32 v16, -v2, v32, v0
	v_fmac_f32_e32 v32, v16, v17
	v_div_fixup_f32 v0, v32, v2, v0
	v_mul_f32_e32 v0, v1, v0
	v_cvt_pk_bf16_f32 v0, v0, v213
	global_store_short v[90:91], v0, off offset:192
	s_waitcnt vmcnt(62)
	v_lshlrev_b32_e32 v0, 16, v161
	v_mul_f32_e32 v2, 0xbfb8aa3b, v0
	v_exp_f32_e32 v2, v2
	v_mul_f32_e32 v1, v3, v154
	v_add_f32_e32 v2, 1.0, v2
	v_rcp_f32_e32 v16, v2
	s_nop 0
	v_mul_f32_e32 v18, v0, v16
	v_fma_f32 v3, -v2, v18, v0
	v_fmac_f32_e32 v18, v3, v16
	v_div_fixup_f32 v0, v18, v2, v0
	v_mul_f32_e32 v0, v1, v0
	v_cvt_pk_bf16_f32 v0, v0, v213
	global_store_short v[88:89], v0, off
	v_lshlrev_b32_e32 v0, 16, v160
	v_mul_f32_e32 v2, 0xbfb8aa3b, v0
	v_exp_f32_e32 v2, v2
	v_mul_f32_e32 v1, v51, v154
	v_add_f32_e32 v2, 1.0, v2
	v_rcp_f32_e32 v16, v2
	s_nop 0
	v_mul_f32_e32 v18, v0, v16
	v_fma_f32 v3, -v2, v18, v0
	v_fmac_f32_e32 v18, v3, v16
	v_div_fixup_f32 v0, v18, v2, v0
	v_mul_f32_e32 v0, v1, v0
	v_cvt_pk_bf16_f32 v0, v0, v213
	global_store_short v[88:89], v0, off offset:64
	s_waitcnt vmcnt(62)
; __device__ __forceinline__ unsigned cvt_pk_bf16(float lo, float hi) { unsigned r; asm volatile("v_cvt_pk_bf16_f32 %0, %1, %2" : "=v"(r) : "v"(lo), "v"(hi)); return r; }
; __device__ __forceinline__ float bf2f(unsigned short b) { return __uint_as_float(((unsigned)b) << 16); }
; __device__ __forceinline__ float silu_f(float z) { return z / (1.f + __expf(-z)); }
; __device__ __forceinline__ void attn_body(const bf16_t* __restrict__ Qb, const bf16_t* __restrict__ Kh, const bf16_t* __restrict__ Vh, const bf16_t* __restrict__ Rh,
;                                           bf16_t* __restrict__ Zb, int seq, char* lds, int wv, bool nowrite) {
;     ...
; #pragma unroll
;     for (int r = 0; r < 16; ++r) {
; #pragma unroll
;         for (int d0 = 0; d0 < 4; ++d0) { const float z = bf2f(zq[r][d0]);
;             if (!nowrite) Zw[(long)((r & 3) + 8 * (r >> 2)) * LDZ + d0 * 32] = (bf16_t)(cvt_pk_bf16(o[d0][r] * rli[r] * silu_f(z), 0.f) & 0xffffu); } }
	v_lshlrev_b32_e32 v0, 16, v158
	v_mul_f32_e32 v2, 0xbfb8aa3b, v0
	v_exp_f32_e32 v2, v2
	v_mul_f32_e32 v1, v35, v154
	v_add_f32_e32 v2, 1.0, v2
	v_rcp_f32_e32 v16, v2
	s_nop 0
	v_mul_f32_e32 v18, v0, v16
	v_fma_f32 v3, -v2, v18, v0
	v_fmac_f32_e32 v18, v3, v16
	v_div_fixup_f32 v0, v18, v2, v0
	v_mul_f32_e32 v0, v1, v0
	v_cvt_pk_bf16_f32 v0, v0, v213
	global_store_short v[88:89], v0, off offset:128
	v_lshlrev_b32_e32 v0, 16, v157
	v_mul_f32_e32 v2, 0xbfb8aa3b, v0
	v_exp_f32_e32 v2, v2
	v_mul_f32_e32 v1, v19, v154
	v_add_f32_e32 v2, 1.0, v2
	v_rcp_f32_e32 v16, v2
	s_nop 0
	v_mul_f32_e32 v18, v0, v16
	v_fma_f32 v3, -v2, v18, v0
	v_fmac_f32_e32 v18, v3, v16
	v_div_fixup_f32 v0, v18, v2, v0
	v_mul_f32_e32 v0, v1, v0
	v_cvt_pk_bf16_f32 v0, v0, v213
	global_store_short v[88:89], v0, off offset:192
	s_waitcnt vmcnt(62)
	v_lshlrev_b32_e32 v0, 16, v156
	v_mul_f32_e32 v2, 0xbfb8aa3b, v0
	v_exp_f32_e32 v2, v2
	v_mul_f32_e32 v1, v4, v149
	v_add_f32_e32 v2, 1.0, v2
	v_rcp_f32_e32 v4, v2
	s_nop 0
	v_mul_f32_e32 v17, v0, v4
	v_fma_f32 v3, -v2, v17, v0
	v_fmac_f32_e32 v17, v3, v4
	v_div_fixup_f32 v0, v17, v2, v0
	v_mul_f32_e32 v0, v1, v0
	v_cvt_pk_bf16_f32 v0, v0, v213
	global_store_short v[84:85], v0, off offset:-4096
	v_lshlrev_b32_e32 v0, 16, v155
	v_mul_f32_e32 v2, 0xbfb8aa3b, v0
	v_exp_f32_e32 v2, v2
	v_mul_f32_e32 v1, v52, v149
	v_add_f32_e32 v2, 1.0, v2
	v_rcp_f32_e32 v4, v2
	s_nop 0
	v_mul_f32_e32 v17, v0, v4
	v_fma_f32 v3, -v2, v17, v0
	v_fmac_f32_e32 v17, v3, v4
	v_div_fixup_f32 v0, v17, v2, v0
	v_mul_f32_e32 v0, v1, v0
	v_cvt_pk_bf16_f32 v0, v0, v213
	global_store_short v[86:87], v0, off offset:64
	s_waitcnt vmcnt(62)
	v_lshlrev_b32_e32 v0, 16, v153
	v_mul_f32_e32 v2, 0xbfb8aa3b, v0
	v_exp_f32_e32 v2, v2
	v_mul_f32_e32 v1, v36, v149
	v_add_f32_e32 v2, 1.0, v2
	v_rcp_f32_e32 v4, v2
	s_nop 0
	v_mul_f32_e32 v17, v0, v4
	v_fma_f32 v3, -v2, v17, v0
	v_fmac_f32_e32 v17, v3, v4
	v_div_fixup_f32 v0, v17, v2, v0
	v_mul_f32_e32 v0, v1, v0
	v_cvt_pk_bf16_f32 v0, v0, v213
	global_store_short v[86:87], v0, off offset:128
	v_lshlrev_b32_e32 v0, 16, v152
	v_mul_f32_e32 v2, 0xbfb8aa3b, v0
	v_exp_f32_e32 v2, v2
	v_mul_f32_e32 v1, v20, v149
	v_add_f32_e32 v2, 1.0, v2
	v_rcp_f32_e32 v4, v2
	s_nop 0
	v_mul_f32_e32 v17, v0, v4
	v_fma_f32 v3, -v2, v17, v0
	v_fmac_f32_e32 v17, v3, v4
	v_div_fixup_f32 v0, v17, v2, v0
	v_mul_f32_e32 v0, v1, v0
	v_cvt_pk_bf16_f32 v0, v0, v213
	global_store_short v[86:87], v0, off offset:192
	s_waitcnt vmcnt(62)
	v_lshlrev_b32_e32 v0, 16, v151
	v_mul_f32_e32 v2, 0xbfb8aa3b, v0
	v_exp_f32_e32 v2, v2
	v_mul_f32_e32 v1, v5, v143
	v_add_f32_e32 v2, 1.0, v2
	v_rcp_f32_e32 v4, v2
	s_nop 0
	v_mul_f32_e32 v16, v0, v4
	v_fma_f32 v3, -v2, v16, v0
	v_fmac_f32_e32 v16, v3, v4
	v_div_fixup_f32 v0, v16, v2, v0
	v_mul_f32_e32 v0, v1, v0
	v_cvt_pk_bf16_f32 v0, v0, v213
	global_store_short v[84:85], v0, off
	v_lshlrev_b32_e32 v0, 16, v150
	v_mul_f32_e32 v2, 0xbfb8aa3b, v0
	v_exp_f32_e32 v2, v2
	v_mul_f32_e32 v1, v53, v143
	v_add_f32_e32 v2, 1.0, v2
	v_rcp_f32_e32 v4, v2
	s_nop 0
	v_mul_f32_e32 v16, v0, v4
	v_fma_f32 v3, -v2, v16, v0
	v_fmac_f32_e32 v16, v3, v4
	v_div_fixup_f32 v0, v16, v2, v0
	v_mul_f32_e32 v0, v1, v0
	v_cvt_pk_bf16_f32 v0, v0, v213
	global_store_short v[84:85], v0, off offset:64
	s_waitcnt vmcnt(62)
	v_lshlrev_b32_e32 v0, 16, v148
	v_mul_f32_e32 v2, 0xbfb8aa3b, v0
	v_exp_f32_e32 v2, v2
	v_mul_f32_e32 v1, v37, v143
	v_add_f32_e32 v2, 1.0, v2
	v_rcp_f32_e32 v4, v2
	s_nop 0
	v_mul_f32_e32 v16, v0, v4
	v_fma_f32 v3, -v2, v16, v0
	v_fmac_f32_e32 v16, v3, v4
	v_div_fixup_f32 v0, v16, v2, v0
	v_mul_f32_e32 v0, v1, v0
	v_cvt_pk_bf16_f32 v0, v0, v213
	global_store_short v[84:85], v0, off offset:128
	v_lshlrev_b32_e32 v0, 16, v147
	v_mul_f32_e32 v2, 0xbfb8aa3b, v0
	v_exp_f32_e32 v2, v2
	v_mul_f32_e32 v1, v21, v143
	v_add_f32_e32 v2, 1.0, v2
	v_rcp_f32_e32 v4, v2
	s_nop 0
	v_mul_f32_e32 v16, v0, v4
	v_fma_f32 v3, -v2, v16, v0
	v_fmac_f32_e32 v16, v3, v4
	v_div_fixup_f32 v0, v16, v2, v0
	v_mul_f32_e32 v0, v1, v0
	v_cvt_pk_bf16_f32 v0, v0, v213
	global_store_short v[84:85], v0, off offset:192
	s_waitcnt vmcnt(62)
	v_lshlrev_b32_e32 v0, 16, v146
	v_mul_f32_e32 v2, 0xbfb8aa3b, v0
	v_exp_f32_e32 v2, v2
	v_mul_f32_e32 v1, v6, v138
	v_add_f32_e32 v2, 1.0, v2
	v_rcp_f32_e32 v4, v2
	s_nop 0
	v_mul_f32_e32 v6, v0, v4
	v_fma_f32 v3, -v2, v6, v0
	v_fmac_f32_e32 v6, v3, v4
	v_div_fixup_f32 v0, v6, v2, v0
	v_mul_f32_e32 v0, v1, v0
	v_cvt_pk_bf16_f32 v0, v0, v213
	global_store_short v[80:81], v0, off offset:-4096
	v_lshlrev_b32_e32 v0, 16, v145
	v_mul_f32_e32 v2, 0xbfb8aa3b, v0
	v_exp_f32_e32 v2, v2
	v_mul_f32_e32 v1, v54, v138
	v_add_f32_e32 v2, 1.0, v2
	v_rcp_f32_e32 v4, v2
	s_nop 0
	v_mul_f32_e32 v6, v0, v4
	v_fma_f32 v3, -v2, v6, v0
	v_fmac_f32_e32 v6, v3, v4
	v_div_fixup_f32 v0, v6, v2, v0
	v_mul_f32_e32 v0, v1, v0
	v_cvt_pk_bf16_f32 v0, v0, v213
	global_store_short v[82:83], v0, off offset:64
	s_waitcnt vmcnt(62)
	v_lshlrev_b32_e32 v0, 16, v144
	v_mul_f32_e32 v2, 0xbfb8aa3b, v0
	v_exp_f32_e32 v2, v2
	v_mul_f32_e32 v1, v38, v138
	v_add_f32_e32 v2, 1.0, v2
	v_rcp_f32_e32 v4, v2
	s_nop 0
	v_mul_f32_e32 v6, v0, v4
	v_fma_f32 v3, -v2, v6, v0
	v_fmac_f32_e32 v6, v3, v4
	v_div_fixup_f32 v0, v6, v2, v0
	v_mul_f32_e32 v0, v1, v0
	v_cvt_pk_bf16_f32 v0, v0, v213
	global_store_short v[82:83], v0, off offset:128
	v_lshlrev_b32_e32 v0, 16, v142
	v_mul_f32_e32 v2, 0xbfb8aa3b, v0
	v_exp_f32_e32 v2, v2
	v_mul_f32_e32 v1, v22, v138
	v_add_f32_e32 v2, 1.0, v2
	v_rcp_f32_e32 v4, v2
	s_nop 0
	v_mul_f32_e32 v6, v0, v4
	v_fma_f32 v3, -v2, v6, v0
	v_fmac_f32_e32 v6, v3, v4
	v_div_fixup_f32 v0, v6, v2, v0
	v_mul_f32_e32 v0, v1, v0
	v_cvt_pk_bf16_f32 v0, v0, v213
	global_store_short v[82:83], v0, off offset:192
	s_waitcnt vmcnt(62)
; __device__ __forceinline__ unsigned cvt_pk_bf16(float lo, float hi) { unsigned r; asm volatile("v_cvt_pk_bf16_f32 %0, %1, %2" : "=v"(r) : "v"(lo), "v"(hi)); return r; }
; __device__ __forceinline__ float bf2f(unsigned short b) { return __uint_as_float(((unsigned)b) << 16); }
; __device__ __forceinline__ float silu_f(float z) { return z / (1.f + __expf(-z)); }
; __device__ __forceinline__ void attn_body(const bf16_t* __restrict__ Qb, const bf16_t* __restrict__ Kh, const bf16_t* __restrict__ Vh, const bf16_t* __restrict__ Rh,
;                                           bf16_t* __restrict__ Zb, int seq, char* lds, int wv, bool nowrite) {
;     ...
; #pragma unroll
;     for (int r = 0; r < 16; ++r) {
; #pragma unroll
;         for (int d0 = 0; d0 < 4; ++d0) { const float z = bf2f(zq[r][d0]);
;             if (!nowrite) Zw[(long)((r & 3) + 8 * (r >> 2)) * LDZ + d0 * 32] = (bf16_t)(cvt_pk_bf16(o[d0][r] * rli[r] * silu_f(z), 0.f) & 0xffffu); } }
	v_lshlrev_b32_e32 v0, 16, v141
	v_mul_f32_e32 v2, 0xbfb8aa3b, v0
	v_exp_f32_e32 v2, v2
	v_mul_f32_e32 v1, v7, v132
	v_add_f32_e32 v2, 1.0, v2
	v_rcp_f32_e32 v4, v2
	s_nop 0
	v_mul_f32_e32 v6, v0, v4
	v_fma_f32 v3, -v2, v6, v0
	v_fmac_f32_e32 v6, v3, v4
	v_div_fixup_f32 v0, v6, v2, v0
	v_mul_f32_e32 v0, v1, v0
	v_cvt_pk_bf16_f32 v0, v0, v213
	global_store_short v[80:81], v0, off
	v_lshlrev_b32_e32 v0, 16, v140
	v_mul_f32_e32 v2, 0xbfb8aa3b, v0
	v_exp_f32_e32 v2, v2
	v_mul_f32_e32 v1, v55, v132
	v_add_f32_e32 v2, 1.0, v2
	v_rcp_f32_e32 v4, v2
	s_nop 0
	v_mul_f32_e32 v6, v0, v4
	v_fma_f32 v3, -v2, v6, v0
	v_fmac_f32_e32 v6, v3, v4
	v_div_fixup_f32 v0, v6, v2, v0
	v_mul_f32_e32 v0, v1, v0
	v_cvt_pk_bf16_f32 v0, v0, v213
	global_store_short v[80:81], v0, off offset:64
	s_waitcnt vmcnt(62)
	v_lshlrev_b32_e32 v0, 16, v139
	v_mul_f32_e32 v2, 0xbfb8aa3b, v0
	v_exp_f32_e32 v2, v2
	v_mul_f32_e32 v1, v39, v132
	v_add_f32_e32 v2, 1.0, v2
	v_rcp_f32_e32 v4, v2
	s_nop 0
	v_mul_f32_e32 v6, v0, v4
	v_fma_f32 v3, -v2, v6, v0
	v_fmac_f32_e32 v6, v3, v4
	v_div_fixup_f32 v0, v6, v2, v0
	v_mul_f32_e32 v0, v1, v0
	v_cvt_pk_bf16_f32 v0, v0, v213
	global_store_short v[80:81], v0, off offset:128
	v_lshlrev_b32_e32 v0, 16, v137
	v_mul_f32_e32 v2, 0xbfb8aa3b, v0
	v_exp_f32_e32 v2, v2
	v_mul_f32_e32 v1, v23, v132
	v_add_f32_e32 v2, 1.0, v2
	v_rcp_f32_e32 v4, v2
	s_nop 0
	v_mul_f32_e32 v6, v0, v4
	v_fma_f32 v3, -v2, v6, v0
	v_fmac_f32_e32 v6, v3, v4
	v_div_fixup_f32 v0, v6, v2, v0
	v_mul_f32_e32 v0, v1, v0
	v_cvt_pk_bf16_f32 v0, v0, v213
	global_store_short v[80:81], v0, off offset:192
	s_waitcnt vmcnt(62)
	v_lshlrev_b32_e32 v0, 16, v136
	v_mul_f32_e32 v2, 0xbfb8aa3b, v0
	v_exp_f32_e32 v2, v2
	v_mul_f32_e32 v1, v8, v127
	v_add_f32_e32 v2, 1.0, v2
	v_rcp_f32_e32 v4, v2
	s_nop 0
	v_mul_f32_e32 v6, v0, v4
	v_fma_f32 v3, -v2, v6, v0
	v_fmac_f32_e32 v6, v3, v4
	v_div_fixup_f32 v0, v6, v2, v0
	v_mul_f32_e32 v0, v1, v0
	v_cvt_pk_bf16_f32 v0, v0, v213
	global_store_short v[76:77], v0, off offset:-4096
	v_lshlrev_b32_e32 v0, 16, v135
	v_mul_f32_e32 v2, 0xbfb8aa3b, v0
	v_exp_f32_e32 v2, v2
	v_mul_f32_e32 v1, v56, v127
	v_add_f32_e32 v2, 1.0, v2
	v_rcp_f32_e32 v4, v2
	s_nop 0
	v_mul_f32_e32 v6, v0, v4
	v_fma_f32 v3, -v2, v6, v0
	v_fmac_f32_e32 v6, v3, v4
	v_div_fixup_f32 v0, v6, v2, v0
	v_mul_f32_e32 v0, v1, v0
	v_cvt_pk_bf16_f32 v0, v0, v213
	global_store_short v[78:79], v0, off offset:64
	s_waitcnt vmcnt(62)
	v_lshlrev_b32_e32 v0, 16, v134
	v_mul_f32_e32 v2, 0xbfb8aa3b, v0
	v_exp_f32_e32 v2, v2
	v_mul_f32_e32 v1, v40, v127
	v_add_f32_e32 v2, 1.0, v2
	v_rcp_f32_e32 v4, v2
	s_nop 0
	v_mul_f32_e32 v6, v0, v4
	v_fma_f32 v3, -v2, v6, v0
	v_fmac_f32_e32 v6, v3, v4
	v_div_fixup_f32 v0, v6, v2, v0
	v_mul_f32_e32 v0, v1, v0
	v_cvt_pk_bf16_f32 v0, v0, v213
	global_store_short v[78:79], v0, off offset:128
	v_lshlrev_b32_e32 v0, 16, v133
	v_mul_f32_e32 v2, 0xbfb8aa3b, v0
	v_exp_f32_e32 v2, v2
	v_mul_f32_e32 v1, v24, v127
	v_add_f32_e32 v2, 1.0, v2
	v_rcp_f32_e32 v4, v2
	s_nop 0
	v_mul_f32_e32 v6, v0, v4
	v_fma_f32 v3, -v2, v6, v0
	v_fmac_f32_e32 v6, v3, v4
	v_div_fixup_f32 v0, v6, v2, v0
	v_mul_f32_e32 v0, v1, v0
	v_cvt_pk_bf16_f32 v0, v0, v213
	global_store_short v[78:79], v0, off offset:192
	s_waitcnt vmcnt(62)
	v_lshlrev_b32_e32 v0, 16, v131
	v_mul_f32_e32 v2, 0xbfb8aa3b, v0
	v_exp_f32_e32 v2, v2
	v_mul_f32_e32 v1, v9, v122
	v_add_f32_e32 v2, 1.0, v2
	v_rcp_f32_e32 v4, v2
	s_nop 0
	v_mul_f32_e32 v6, v0, v4
	v_fma_f32 v3, -v2, v6, v0
	v_fmac_f32_e32 v6, v3, v4
	v_div_fixup_f32 v0, v6, v2, v0
	v_mul_f32_e32 v0, v1, v0
	v_cvt_pk_bf16_f32 v0, v0, v213
	global_store_short v[76:77], v0, off
	v_lshlrev_b32_e32 v0, 16, v130
	v_mul_f32_e32 v2, 0xbfb8aa3b, v0
	v_exp_f32_e32 v2, v2
	v_mul_f32_e32 v1, v57, v122
	v_add_f32_e32 v2, 1.0, v2
	v_rcp_f32_e32 v4, v2
	s_nop 0
	v_mul_f32_e32 v6, v0, v4
	v_fma_f32 v3, -v2, v6, v0
	v_fmac_f32_e32 v6, v3, v4
	v_div_fixup_f32 v0, v6, v2, v0
	v_mul_f32_e32 v0, v1, v0
	v_cvt_pk_bf16_f32 v0, v0, v213
	global_store_short v[76:77], v0, off offset:64
	s_waitcnt vmcnt(62)
	v_lshlrev_b32_e32 v0, 16, v129
	v_mul_f32_e32 v2, 0xbfb8aa3b, v0
	v_exp_f32_e32 v2, v2
	v_mul_f32_e32 v1, v41, v122
	v_add_f32_e32 v2, 1.0, v2
	v_rcp_f32_e32 v4, v2
	s_nop 0
	v_mul_f32_e32 v6, v0, v4
	v_fma_f32 v3, -v2, v6, v0
	v_fmac_f32_e32 v6, v3, v4
	v_div_fixup_f32 v0, v6, v2, v0
	v_mul_f32_e32 v0, v1, v0
	v_cvt_pk_bf16_f32 v0, v0, v213
	global_store_short v[76:77], v0, off offset:128
	v_lshlrev_b32_e32 v0, 16, v128
	v_mul_f32_e32 v2, 0xbfb8aa3b, v0
	v_exp_f32_e32 v2, v2
	v_mul_f32_e32 v1, v25, v122
	v_add_f32_e32 v2, 1.0, v2
	v_rcp_f32_e32 v4, v2
	s_nop 0
	v_mul_f32_e32 v6, v0, v4
	v_fma_f32 v3, -v2, v6, v0
	v_fmac_f32_e32 v6, v3, v4
	v_div_fixup_f32 v0, v6, v2, v0
	v_mul_f32_e32 v0, v1, v0
	v_cvt_pk_bf16_f32 v0, v0, v213
	global_store_short v[76:77], v0, off offset:192
	s_waitcnt vmcnt(62)
	v_lshlrev_b32_e32 v0, 16, v126
	v_mul_f32_e32 v2, 0xbfb8aa3b, v0
	v_exp_f32_e32 v2, v2
	v_mul_f32_e32 v1, v10, v116
	v_add_f32_e32 v2, 1.0, v2
	v_rcp_f32_e32 v4, v2
	s_nop 0
	v_mul_f32_e32 v6, v0, v4
	v_fma_f32 v3, -v2, v6, v0
	v_fmac_f32_e32 v6, v3, v4
	v_div_fixup_f32 v0, v6, v2, v0
	v_mul_f32_e32 v0, v1, v0
	v_cvt_pk_bf16_f32 v0, v0, v213
	global_store_short v[72:73], v0, off offset:-4096
	v_lshlrev_b32_e32 v0, 16, v125
	v_mul_f32_e32 v2, 0xbfb8aa3b, v0
	v_exp_f32_e32 v2, v2
	v_mul_f32_e32 v1, v58, v116
	v_add_f32_e32 v2, 1.0, v2
	v_rcp_f32_e32 v4, v2
	s_nop 0
	v_mul_f32_e32 v6, v0, v4
	v_fma_f32 v3, -v2, v6, v0
	v_fmac_f32_e32 v6, v3, v4
	v_div_fixup_f32 v0, v6, v2, v0
	v_mul_f32_e32 v0, v1, v0
	v_cvt_pk_bf16_f32 v0, v0, v213
	global_store_short v[74:75], v0, off offset:64
	s_waitcnt vmcnt(62)
; __device__ __forceinline__ unsigned cvt_pk_bf16(float lo, float hi) { unsigned r; asm volatile("v_cvt_pk_bf16_f32 %0, %1, %2" : "=v"(r) : "v"(lo), "v"(hi)); return r; }
; __device__ __forceinline__ float bf2f(unsigned short b) { return __uint_as_float(((unsigned)b) << 16); }
; __device__ __forceinline__ float silu_f(float z) { return z / (1.f + __expf(-z)); }
; __device__ __forceinline__ void attn_body(const bf16_t* __restrict__ Qb, const bf16_t* __restrict__ Kh, const bf16_t* __restrict__ Vh, const bf16_t* __restrict__ Rh,
;                                           bf16_t* __restrict__ Zb, int seq, char* lds, int wv, bool nowrite) {
;     ...
; #pragma unroll
;     for (int r = 0; r < 16; ++r) {
; #pragma unroll
;         for (int d0 = 0; d0 < 4; ++d0) { const float z = bf2f(zq[r][d0]);
;             if (!nowrite) Zw[(long)((r & 3) + 8 * (r >> 2)) * LDZ + d0 * 32] = (bf16_t)(cvt_pk_bf16(o[d0][r] * rli[r] * silu_f(z), 0.f) & 0xffffu); } }
	v_lshlrev_b32_e32 v0, 16, v124
	v_mul_f32_e32 v2, 0xbfb8aa3b, v0
	v_exp_f32_e32 v2, v2
	v_mul_f32_e32 v1, v42, v116
	v_add_f32_e32 v2, 1.0, v2
	v_rcp_f32_e32 v4, v2
	s_nop 0
	v_mul_f32_e32 v6, v0, v4
	v_fma_f32 v3, -v2, v6, v0
	v_fmac_f32_e32 v6, v3, v4
	v_div_fixup_f32 v0, v6, v2, v0
	v_mul_f32_e32 v0, v1, v0
	v_cvt_pk_bf16_f32 v0, v0, v213
	global_store_short v[74:75], v0, off offset:128
	v_lshlrev_b32_e32 v0, 16, v123
	v_mul_f32_e32 v2, 0xbfb8aa3b, v0
	v_exp_f32_e32 v2, v2
	v_mul_f32_e32 v1, v26, v116
	v_add_f32_e32 v2, 1.0, v2
	v_rcp_f32_e32 v4, v2
	s_nop 0
	v_mul_f32_e32 v6, v0, v4
	v_fma_f32 v3, -v2, v6, v0
	v_fmac_f32_e32 v6, v3, v4
	v_div_fixup_f32 v0, v6, v2, v0
	v_mul_f32_e32 v0, v1, v0
	v_cvt_pk_bf16_f32 v0, v0, v213
	global_store_short v[74:75], v0, off offset:192
	s_waitcnt vmcnt(62)
	v_lshlrev_b32_e32 v0, 16, v121
	v_mul_f32_e32 v2, 0xbfb8aa3b, v0
	v_exp_f32_e32 v2, v2
	v_mul_f32_e32 v1, v11, v111
	v_add_f32_e32 v2, 1.0, v2
	v_rcp_f32_e32 v4, v2
	s_nop 0
	v_mul_f32_e32 v6, v0, v4
	v_fma_f32 v3, -v2, v6, v0
	v_fmac_f32_e32 v6, v3, v4
	v_div_fixup_f32 v0, v6, v2, v0
	v_mul_f32_e32 v0, v1, v0
	v_cvt_pk_bf16_f32 v0, v0, v213
	global_store_short v[72:73], v0, off
	v_lshlrev_b32_e32 v0, 16, v120
	v_mul_f32_e32 v2, 0xbfb8aa3b, v0
	v_exp_f32_e32 v2, v2
	v_mul_f32_e32 v1, v59, v111
	v_add_f32_e32 v2, 1.0, v2
	v_rcp_f32_e32 v4, v2
	s_nop 0
	v_mul_f32_e32 v6, v0, v4
	v_fma_f32 v3, -v2, v6, v0
	v_fmac_f32_e32 v6, v3, v4
	v_div_fixup_f32 v0, v6, v2, v0
	v_mul_f32_e32 v0, v1, v0
	v_cvt_pk_bf16_f32 v0, v0, v213
	global_store_short v[72:73], v0, off offset:64
	s_waitcnt vmcnt(62)
	v_lshlrev_b32_e32 v0, 16, v119
	v_mul_f32_e32 v2, 0xbfb8aa3b, v0
	v_exp_f32_e32 v2, v2
	v_mul_f32_e32 v1, v43, v111
	v_add_f32_e32 v2, 1.0, v2
	v_rcp_f32_e32 v4, v2
	s_nop 0
	v_mul_f32_e32 v6, v0, v4
	v_fma_f32 v3, -v2, v6, v0
	v_fmac_f32_e32 v6, v3, v4
	v_div_fixup_f32 v0, v6, v2, v0
	v_mul_f32_e32 v0, v1, v0
	v_cvt_pk_bf16_f32 v0, v0, v213
	global_store_short v[72:73], v0, off offset:128
	v_lshlrev_b32_e32 v0, 16, v118
	v_mul_f32_e32 v2, 0xbfb8aa3b, v0
	v_exp_f32_e32 v2, v2
	v_mul_f32_e32 v1, v27, v111
	v_add_f32_e32 v2, 1.0, v2
	v_rcp_f32_e32 v4, v2
	s_nop 0
	v_mul_f32_e32 v6, v0, v4
	v_fma_f32 v3, -v2, v6, v0
	v_fmac_f32_e32 v6, v3, v4
	v_div_fixup_f32 v0, v6, v2, v0
	v_mul_f32_e32 v0, v1, v0
	v_cvt_pk_bf16_f32 v0, v0, v213
	global_store_short v[72:73], v0, off offset:192
	s_waitcnt vmcnt(62)
	v_lshlrev_b32_e32 v0, 16, v117
	v_mul_f32_e32 v2, 0xbfb8aa3b, v0
	v_exp_f32_e32 v2, v2
	v_mul_f32_e32 v1, v12, v105
	v_add_f32_e32 v2, 1.0, v2
	v_rcp_f32_e32 v4, v2
	s_nop 0
	v_mul_f32_e32 v6, v0, v4
	v_fma_f32 v3, -v2, v6, v0
	v_fmac_f32_e32 v6, v3, v4
	v_div_fixup_f32 v0, v6, v2, v0
	v_mul_f32_e32 v0, v1, v0
	v_cvt_pk_bf16_f32 v0, v0, v213
	global_store_short v[68:69], v0, off offset:-4096
	v_lshlrev_b32_e32 v0, 16, v115
	v_mul_f32_e32 v2, 0xbfb8aa3b, v0
	v_exp_f32_e32 v2, v2
	v_mul_f32_e32 v1, v60, v105
	v_add_f32_e32 v2, 1.0, v2
	v_rcp_f32_e32 v4, v2
	s_nop 0
	v_mul_f32_e32 v6, v0, v4
	v_fma_f32 v3, -v2, v6, v0
	v_fmac_f32_e32 v6, v3, v4
	v_div_fixup_f32 v0, v6, v2, v0
	v_mul_f32_e32 v0, v1, v0
	v_cvt_pk_bf16_f32 v0, v0, v213
	global_store_short v[70:71], v0, off offset:64
	s_waitcnt vmcnt(62)
	v_lshlrev_b32_e32 v0, 16, v114
	v_mul_f32_e32 v2, 0xbfb8aa3b, v0
	v_exp_f32_e32 v2, v2
	v_mul_f32_e32 v1, v44, v105
	v_add_f32_e32 v2, 1.0, v2
	v_rcp_f32_e32 v4, v2
	s_nop 0
	v_mul_f32_e32 v6, v0, v4
	v_fma_f32 v3, -v2, v6, v0
	v_fmac_f32_e32 v6, v3, v4
	v_div_fixup_f32 v0, v6, v2, v0
	v_mul_f32_e32 v0, v1, v0
	v_cvt_pk_bf16_f32 v0, v0, v213
	global_store_short v[70:71], v0, off offset:128
	v_lshlrev_b32_e32 v0, 16, v113
	v_mul_f32_e32 v2, 0xbfb8aa3b, v0
	v_exp_f32_e32 v2, v2
	v_mul_f32_e32 v1, v28, v105
	v_add_f32_e32 v2, 1.0, v2
	v_rcp_f32_e32 v4, v2
	s_nop 0
	v_mul_f32_e32 v6, v0, v4
	v_fma_f32 v3, -v2, v6, v0
	v_fmac_f32_e32 v6, v3, v4
	v_div_fixup_f32 v0, v6, v2, v0
	v_mul_f32_e32 v0, v1, v0
	v_cvt_pk_bf16_f32 v0, v0, v213
	global_store_short v[70:71], v0, off offset:192
	s_waitcnt vmcnt(62)
	v_lshlrev_b32_e32 v0, 16, v112
	v_mul_f32_e32 v2, 0xbfb8aa3b, v0
	v_exp_f32_e32 v2, v2
	v_mul_f32_e32 v1, v13, v100
	v_add_f32_e32 v2, 1.0, v2
	v_rcp_f32_e32 v4, v2
	s_nop 0
	v_mul_f32_e32 v6, v0, v4
	v_fma_f32 v3, -v2, v6, v0
	v_fmac_f32_e32 v6, v3, v4
	v_div_fixup_f32 v0, v6, v2, v0
	v_mul_f32_e32 v0, v1, v0
	v_cvt_pk_bf16_f32 v0, v0, v213
	global_store_short v[68:69], v0, off
	v_lshlrev_b32_e32 v0, 16, v110
	v_mul_f32_e32 v2, 0xbfb8aa3b, v0
	v_exp_f32_e32 v2, v2
	v_mul_f32_e32 v1, v61, v100
	v_add_f32_e32 v2, 1.0, v2
	v_rcp_f32_e32 v4, v2
	s_nop 0
	v_mul_f32_e32 v6, v0, v4
	v_fma_f32 v3, -v2, v6, v0
	v_fmac_f32_e32 v6, v3, v4
	v_div_fixup_f32 v0, v6, v2, v0
	v_mul_f32_e32 v0, v1, v0
	v_cvt_pk_bf16_f32 v0, v0, v213
	global_store_short v[68:69], v0, off offset:64
	s_waitcnt vmcnt(62)
; __device__ __forceinline__ unsigned cvt_pk_bf16(float lo, float hi) { unsigned r; asm volatile("v_cvt_pk_bf16_f32 %0, %1, %2" : "=v"(r) : "v"(lo), "v"(hi)); return r; }
; __device__ __forceinline__ float bf2f(unsigned short b) { return __uint_as_float(((unsigned)b) << 16); }
; __device__ __forceinline__ float silu_f(float z) { return z / (1.f + __expf(-z)); }
; __device__ __forceinline__ void attn_body(const bf16_t* __restrict__ Qb, const bf16_t* __restrict__ Kh, const bf16_t* __restrict__ Vh, const bf16_t* __restrict__ Rh,
;                                           bf16_t* __restrict__ Zb, int seq, char* lds, int wv, bool nowrite) {
;     ...
; #pragma unroll
;     for (int r = 0; r < 16; ++r) {
; #pragma unroll
;         for (int d0 = 0; d0 < 4; ++d0) { const float z = bf2f(zq[r][d0]);
;             if (!nowrite) Zw[(long)((r & 3) + 8 * (r >> 2)) * LDZ + d0 * 32] = (bf16_t)(cvt_pk_bf16(o[d0][r] * rli[r] * silu_f(z), 0.f) & 0xffffu); } }
;     __syncthreads();
	v_lshlrev_b32_e32 v0, 16, v109
	v_mul_f32_e32 v2, 0xbfb8aa3b, v0
	v_exp_f32_e32 v2, v2
	v_mul_f32_e32 v1, v45, v100
	v_add_f32_e32 v2, 1.0, v2
	v_rcp_f32_e32 v4, v2
	s_nop 0
	v_mul_f32_e32 v6, v0, v4
	v_fma_f32 v3, -v2, v6, v0
	v_fmac_f32_e32 v6, v3, v4
	v_div_fixup_f32 v0, v6, v2, v0
	v_mul_f32_e32 v0, v1, v0
	v_cvt_pk_bf16_f32 v0, v0, v213
	global_store_short v[68:69], v0, off offset:128
	v_lshlrev_b32_e32 v0, 16, v108
	v_mul_f32_e32 v2, 0xbfb8aa3b, v0
	v_exp_f32_e32 v2, v2
	v_mul_f32_e32 v1, v29, v100
	v_add_f32_e32 v2, 1.0, v2
	v_rcp_f32_e32 v4, v2
	s_nop 0
	v_mul_f32_e32 v6, v0, v4
	v_fma_f32 v3, -v2, v6, v0
	v_fmac_f32_e32 v6, v3, v4
	v_div_fixup_f32 v0, v6, v2, v0
	v_mul_f32_e32 v0, v1, v0
	v_cvt_pk_bf16_f32 v0, v0, v213
	global_store_short v[68:69], v0, off offset:192
	s_waitcnt vmcnt(62)
	v_lshlrev_b32_e32 v0, 16, v107
	v_mul_f32_e32 v2, 0xbfb8aa3b, v0
	v_exp_f32_e32 v2, v2
	v_mul_f32_e32 v1, v14, v97
	v_add_f32_e32 v2, 1.0, v2
	v_rcp_f32_e32 v4, v2
	s_nop 0
	v_mul_f32_e32 v6, v0, v4
	v_fma_f32 v3, -v2, v6, v0
	v_fmac_f32_e32 v6, v3, v4
	v_div_fixup_f32 v0, v6, v2, v0
	v_mul_f32_e32 v0, v1, v0
	v_cvt_pk_bf16_f32 v0, v0, v213
	global_store_short v[64:65], v0, off offset:-4096
	v_lshlrev_b32_e32 v0, 16, v106
	v_mul_f32_e32 v2, 0xbfb8aa3b, v0
	v_exp_f32_e32 v2, v2
	v_mul_f32_e32 v1, v62, v97
	v_add_f32_e32 v2, 1.0, v2
	v_rcp_f32_e32 v4, v2
	s_nop 0
	v_mul_f32_e32 v6, v0, v4
	v_fma_f32 v3, -v2, v6, v0
	v_fmac_f32_e32 v6, v3, v4
	v_div_fixup_f32 v0, v6, v2, v0
	v_mul_f32_e32 v0, v1, v0
	v_cvt_pk_bf16_f32 v0, v0, v213
	global_store_short v[66:67], v0, off offset:64
	s_waitcnt vmcnt(62)
	v_lshlrev_b32_e32 v0, 16, v104
	v_mul_f32_e32 v2, 0xbfb8aa3b, v0
	v_exp_f32_e32 v2, v2
	v_mul_f32_e32 v1, v46, v97
	v_add_f32_e32 v2, 1.0, v2
	v_rcp_f32_e32 v4, v2
	s_nop 0
	v_mul_f32_e32 v6, v0, v4
	v_fma_f32 v3, -v2, v6, v0
	v_fmac_f32_e32 v6, v3, v4
	v_div_fixup_f32 v0, v6, v2, v0
	v_mul_f32_e32 v0, v1, v0
	v_cvt_pk_bf16_f32 v0, v0, v213
	global_store_short v[66:67], v0, off offset:128
	v_lshlrev_b32_e32 v0, 16, v103
	v_mul_f32_e32 v2, 0xbfb8aa3b, v0
	v_exp_f32_e32 v2, v2
	v_mul_f32_e32 v1, v30, v97
	v_add_f32_e32 v2, 1.0, v2
	v_rcp_f32_e32 v4, v2
	s_nop 0
	v_mul_f32_e32 v6, v0, v4
	v_fma_f32 v3, -v2, v6, v0
	v_fmac_f32_e32 v6, v3, v4
	v_div_fixup_f32 v0, v6, v2, v0
	v_mul_f32_e32 v0, v1, v0
	v_cvt_pk_bf16_f32 v0, v0, v213
	global_store_short v[66:67], v0, off offset:192
	s_waitcnt vmcnt(62)
	v_lshlrev_b32_e32 v0, 16, v102
	v_mul_f32_e32 v2, 0xbfb8aa3b, v0
	v_exp_f32_e32 v2, v2
	v_mul_f32_e32 v1, v15, v96
	v_add_f32_e32 v2, 1.0, v2
	v_rcp_f32_e32 v4, v2
	s_nop 0
	v_mul_f32_e32 v6, v0, v4
	v_fma_f32 v3, -v2, v6, v0
	v_fmac_f32_e32 v6, v3, v4
	v_div_fixup_f32 v0, v6, v2, v0
	v_mul_f32_e32 v0, v1, v0
	v_cvt_pk_bf16_f32 v0, v0, v213
	global_store_short v[64:65], v0, off
	v_lshlrev_b32_e32 v0, 16, v101
	v_mul_f32_e32 v2, 0xbfb8aa3b, v0
	v_exp_f32_e32 v2, v2
	v_mul_f32_e32 v1, v63, v96
	v_add_f32_e32 v2, 1.0, v2
	v_rcp_f32_e32 v4, v2
	s_nop 0
	v_mul_f32_e32 v6, v0, v4
	v_fma_f32 v3, -v2, v6, v0
	v_fmac_f32_e32 v6, v3, v4
	v_div_fixup_f32 v0, v6, v2, v0
	v_mul_f32_e32 v0, v1, v0
	v_cvt_pk_bf16_f32 v0, v0, v213
	global_store_short v[64:65], v0, off offset:64
	s_waitcnt vmcnt(62)
	v_lshlrev_b32_e32 v0, 16, v99
	v_mul_f32_e32 v2, 0xbfb8aa3b, v0
	v_exp_f32_e32 v2, v2
	v_mul_f32_e32 v1, v47, v96
	v_add_f32_e32 v2, 1.0, v2
	v_rcp_f32_e32 v4, v2
	s_nop 0
	v_mul_f32_e32 v6, v0, v4
	v_fma_f32 v3, -v2, v6, v0
	v_fmac_f32_e32 v6, v3, v4
	v_div_fixup_f32 v0, v6, v2, v0
	v_mul_f32_e32 v0, v1, v0
	v_cvt_pk_bf16_f32 v0, v0, v213
	global_store_short v[64:65], v0, off offset:128
	v_lshlrev_b32_e32 v0, 16, v98
	v_mul_f32_e32 v2, 0xbfb8aa3b, v0
	v_exp_f32_e32 v2, v2
	v_mul_f32_e32 v1, v31, v96
	v_add_f32_e32 v2, 1.0, v2
	v_rcp_f32_e32 v4, v2
	s_nop 0
	v_mul_f32_e32 v6, v0, v4
	v_fma_f32 v3, -v2, v6, v0
	v_fmac_f32_e32 v6, v3, v4
	v_div_fixup_f32 v0, v6, v2, v0
	v_mul_f32_e32 v0, v1, v0
	v_cvt_pk_bf16_f32 v0, v0, v213
	global_store_short v[64:65], v0, off offset:192
	s_waitcnt vmcnt(63) expcnt(7) lgkmcnt(15)
	s_barrier
	s_cbranch_scc1 .LBB0_624
